# FFN-up epilogue: first eight conv-weight loads issued before the LDS-exchange barrier (wait/barrier moved toward first consumer)
# speedup vs baseline: 1.0026x; 1.0026x over previous
.LBB0_1345:
	s_or_b64 exec, exec, s[10:11]
	v_lshl_or_b32 v112, s56, 7, v211
	v_ashrrev_i32_e32 v113, 31, v112
	v_readlane_b32 s10, v255, 18
	v_lshlrev_b64 v[104:105], 2, v[112:113]
	v_readlane_b32 s11, v255, 19
	v_lshl_add_u64 v[98:99], s[52:53], 0, v[104:105]
	v_lshl_add_u64 v[120:121], s[22:23], 0, v[104:105]
	v_lshl_add_u64 v[100:101], s[10:11], 0, v[104:105]
	v_lshl_add_u64 v[116:117], s[76:77], 0, v[104:105]
	v_lshl_add_u64 v[118:119], s[28:29], 0, v[104:105]
	global_load_dwordx2 v[202:203], v[98:99], off
	global_load_dwordx2 v[204:205], v[116:117], off
	global_load_dwordx2 v[200:201], v[118:119], off
	global_load_dwordx2 v[206:207], v[100:101], off
	v_lshl_add_u64 v[124:125], s[74:75], 0, v[104:105]
	v_lshl_add_u64 v[128:129], s[34:35], 0, v[104:105]
	global_load_dwordx2 v[192:193], v[120:121], off
	global_load_dwordx2 v[194:195], v[124:125], off
	global_load_dwordx2 v[148:149], v[128:129], off
	v_lshl_add_u64 v[132:133], s[58:59], 0, v[104:105]
	global_load_dwordx2 v[196:197], v[132:133], off
	s_waitcnt lgkmcnt(0)
	s_barrier
	v_readlane_b32 s10, v255, 20
	v_cndmask_b32_e64 v104, 0, 1, s[60:61]
	v_mov_b32_e32 v165, 0
	v_lshl_add_u32 v208, v220, 3, s10
	v_cmp_ne_u32_e64 s[10:11], 1, v104
	s_andn2_b64 vcc, exec, s[60:61]
	v_mov_b32_e32 v245, 0
	s_cbranch_vccnz .LBB0_1347
	ds_read_b32 v245, v208 offset:128
